# x tile of the P3 residual epilogue prefetched (touched) by each workgroup before grid barrier 3; P3 x loads default policy
# baseline (speedup 1.0000x reference)
.LBB0_311:
	s_cmpk_gt_u32 s2, 0xff
	s_cbranch_scc1 .Lxpf_skip
	v_readfirstlane_b32 s4, v254
	s_and_b32 s5, s2, 7
	s_lshr_b32 s4, s4, 6
	s_lshl_b32 s5, s5, 3
	s_bfe_u32 s6, s2, 0x30003
	s_add_i32 s5, s5, s6
	s_lshr_b32 s6, s2, 6
	s_lshl_b32 s5, s5, 20
	s_lshl_b32 s6, s6, 10
	s_add_i32 s5, s5, s6
	s_lshl_b32 s4, s4, 17
	s_add_i32 s5, s5, s4
	v_and_b32_e32 v240, 63, v254
	v_lshrrev_b32_e32 v241, 3, v240
	v_and_b32_e32 v240, 7, v240
	v_lshlrev_b32_e32 v241, 12, v241
	v_lshl_or_b32 v240, v240, 7, v241
	v_add_u32_e32 v240, s5, v240
	global_load_dword v242, v240, s[12:13]
	v_add_u32_e32 v241, 0x8000, v240
	global_load_dword v243, v241, s[12:13]
	v_add_u32_e32 v241, 0x10000, v240
	global_load_dword v244, v241, s[12:13]
	v_add_u32_e32 v241, 0x18000, v240
	global_load_dword v245, v241, s[12:13]
